# adds: RG-LRU local scan from registers (all LDS reads up front, SGPR row bases); attention P.V fragment reads batched per 4-MFMA group
# baseline (speedup 1.0000x reference)
.LBB0_645:
	s_movk_i32 s6, 0x190
	v_mad_u64_u32 v[22:23], s[6:7], v77, s6, v[78:79]
	v_add_u32_e32 v21, 0xc800, v22
	v_cvt_pk_bf16_f32 v68, v103, v104
	v_cvt_pk_bf16_f32 v69, v105, v106
	v_cvt_pk_bf16_f32 v70, v107, v108
	v_cvt_pk_bf16_f32 v71, v109, v110
	ds_read2_b64 v[72:75], v21 offset0:136 offset1:140
	v_add_u32_e32 v21, 0xe000, v22
	ds_read2_b64 v[164:167], v21 offset0:168 offset1:172
	v_add_u32_e32 v21, 0xf800, v22
	ds_read2_b64 v[168:171], v21 offset0:200 offset1:204
	v_add_u32_e32 v21, 0xcc40, v22
	v_add_u32_e32 v21, 0x4800, v21
	ds_read2_b64 v[172:175], v21 offset0:96 offset1:100
	s_waitcnt lgkmcnt(3)
	v_mfma_f32_16x16x32_bf16 v[40:43], v[72:75], v[68:71], v[40:43]
	s_waitcnt lgkmcnt(2)
	v_mfma_f32_16x16x32_bf16 v[36:39], v[164:167], v[68:71], v[36:39]
	s_waitcnt lgkmcnt(1)
	v_mfma_f32_16x16x32_bf16 v[32:35], v[168:171], v[68:71], v[32:35]
	s_waitcnt lgkmcnt(0)
	v_mfma_f32_16x16x32_bf16 v[28:31], v[172:175], v[68:71], v[28:31]
.LBB0_646:
	s_cmp_gt_i32 s24, 2
	s_cselect_b64 s[6:7], -1, 0
	s_cmp_lt_i32 s24, 3
	s_cbranch_scc1 .LBB0_650
	s_movk_i32 s8, 0x190
	v_mad_u64_u32 v[22:23], s[8:9], v77, s8, v[78:79]
	v_add_u32_e32 v21, 0xc800, v22
	v_cvt_pk_bf16_f32 v68, v95, v96
	v_cvt_pk_bf16_f32 v69, v97, v98
	v_cvt_pk_bf16_f32 v70, v99, v100
	v_cvt_pk_bf16_f32 v71, v101, v102
	ds_read2_b64 v[72:75], v21 offset0:144 offset1:148
	v_add_u32_e32 v21, 0xe000, v22
	ds_read2_b64 v[164:167], v21 offset0:176 offset1:180
	v_add_u32_e32 v21, 0xf800, v22
	ds_read2_b64 v[168:171], v21 offset0:208 offset1:212
	v_add_u32_e32 v21, 0xcc80, v22
	v_add_u32_e32 v21, 0x4800, v21
	ds_read2_b64 v[172:175], v21 offset0:96 offset1:100
	s_waitcnt lgkmcnt(3)
	v_mfma_f32_16x16x32_bf16 v[40:43], v[72:75], v[68:71], v[40:43]
	s_waitcnt lgkmcnt(2)
	v_mfma_f32_16x16x32_bf16 v[36:39], v[164:167], v[68:71], v[36:39]
	s_waitcnt lgkmcnt(1)
	v_mfma_f32_16x16x32_bf16 v[32:35], v[168:171], v[68:71], v[32:35]
	s_waitcnt lgkmcnt(0)
	v_mfma_f32_16x16x32_bf16 v[28:31], v[172:175], v[68:71], v[28:31]
	s_cmp_gt_i32 s24, 3
	s_cselect_b64 s[8:9], -1, 0
	s_cmp_lt_i32 s24, 4
	s_cbranch_scc0 .LBB0_651

.LBB0_649:
	s_movk_i32 s12, 0x190
	v_mad_u64_u32 v[22:23], s[12:13], v77, s12, v[78:79]
	v_add_u32_e32 v21, 0xc800, v22
	v_cvt_pk_bf16_f32 v54, v54, v55
	v_cvt_pk_bf16_f32 v55, v56, v57
	v_cvt_pk_bf16_f32 v56, v58, v59
	v_cvt_pk_bf16_f32 v57, v60, v61
	ds_read2_b64 v[58:61], v21 offset0:160 offset1:164
	v_add_u32_e32 v21, 0xe000, v22
	ds_read2_b64 v[164:167], v21 offset0:192 offset1:196
	v_add_u32_e32 v21, 0xf800, v22
	ds_read2_b64 v[168:171], v21 offset0:224 offset1:228
	v_add_u32_e32 v21, 0xcd00, v22
	v_add_u32_e32 v21, 0x4800, v21
	ds_read2_b64 v[172:175], v21 offset0:96 offset1:100
	s_waitcnt lgkmcnt(3)
	v_mfma_f32_16x16x32_bf16 v[40:43], v[58:61], v[54:57], v[40:43]
	s_waitcnt lgkmcnt(2)
	v_mfma_f32_16x16x32_bf16 v[36:39], v[164:167], v[54:57], v[36:39]
	s_waitcnt lgkmcnt(1)
	v_mfma_f32_16x16x32_bf16 v[32:35], v[168:171], v[54:57], v[32:35]
	s_waitcnt lgkmcnt(0)
	v_mfma_f32_16x16x32_bf16 v[28:31], v[172:175], v[54:57], v[28:31]
	s_cmp_gt_i32 s24, 5
	s_cselect_b64 s[12:13], -1, 0
	s_cmp_lt_i32 s24, 6
	s_cbranch_scc0 .LBB0_653
	s_branch .LBB0_654

.LBB0_651:
	s_movk_i32 s10, 0x190
	v_mad_u64_u32 v[22:23], s[10:11], v77, s10, v[78:79]
	v_add_u32_e32 v21, 0xc800, v22
	v_cvt_pk_bf16_f32 v62, v62, v63
	v_cvt_pk_bf16_f32 v63, v64, v65
	v_cvt_pk_bf16_f32 v64, v66, v67
	v_cvt_pk_bf16_f32 v65, v93, v94
	ds_read2_b64 v[66:69], v21 offset0:152 offset1:156
	v_add_u32_e32 v21, 0xe000, v22
	ds_read2_b64 v[164:167], v21 offset0:184 offset1:188
	v_add_u32_e32 v21, 0xf800, v22
	ds_read2_b64 v[168:171], v21 offset0:216 offset1:220
	v_add_u32_e32 v21, 0xccc0, v22
	v_add_u32_e32 v21, 0x4800, v21
	ds_read2_b64 v[172:175], v21 offset0:96 offset1:100
	s_waitcnt lgkmcnt(3)
	v_mfma_f32_16x16x32_bf16 v[40:43], v[66:69], v[62:65], v[40:43]
	s_waitcnt lgkmcnt(2)
	v_mfma_f32_16x16x32_bf16 v[36:39], v[164:167], v[62:65], v[36:39]
	s_waitcnt lgkmcnt(1)
	v_mfma_f32_16x16x32_bf16 v[32:35], v[168:171], v[62:65], v[32:35]
	s_waitcnt lgkmcnt(0)
	v_mfma_f32_16x16x32_bf16 v[28:31], v[172:175], v[62:65], v[28:31]
	s_cmp_gt_i32 s24, 4
	s_cselect_b64 s[10:11], -1, 0
	s_cmp_lt_i32 s24, 5
	s_cbranch_scc0 .LBB0_649

.LBB0_653:
	s_movk_i32 s16, 0x190
	v_mad_u64_u32 v[22:23], s[16:17], v77, s16, v[78:79]
	v_add_u32_e32 v21, 0xc800, v22
	v_cvt_pk_bf16_f32 v46, v46, v47
	v_cvt_pk_bf16_f32 v47, v48, v49
	v_cvt_pk_bf16_f32 v48, v50, v51
	v_cvt_pk_bf16_f32 v49, v52, v53
	ds_read2_b64 v[50:53], v21 offset0:168 offset1:172
	v_add_u32_e32 v21, 0xe000, v22
	ds_read2_b64 v[164:167], v21 offset0:200 offset1:204
	v_add_u32_e32 v21, 0xf800, v22
	ds_read2_b64 v[168:171], v21 offset0:232 offset1:236
	v_add_u32_e32 v21, 0xcd40, v22
	v_add_u32_e32 v21, 0x4800, v21
	ds_read2_b64 v[172:175], v21 offset0:96 offset1:100
	s_waitcnt lgkmcnt(3)
	v_mfma_f32_16x16x32_bf16 v[40:43], v[50:53], v[46:49], v[40:43]
	s_waitcnt lgkmcnt(2)
	v_mfma_f32_16x16x32_bf16 v[36:39], v[164:167], v[46:49], v[36:39]
	s_waitcnt lgkmcnt(1)
	v_mfma_f32_16x16x32_bf16 v[32:35], v[168:171], v[46:49], v[32:35]
	s_waitcnt lgkmcnt(0)
	v_mfma_f32_16x16x32_bf16 v[28:31], v[172:175], v[46:49], v[28:31]

.LBB0_683:
	s_movk_i32 s14, 0x190
	v_mad_u64_u32 v[22:23], s[14:15], v77, s14, v[78:79]
	v_add_u32_e32 v21, 0xc800, v22
	v_cvt_pk_bf16_f32 v56, v115, v116
	v_cvt_pk_bf16_f32 v57, v117, v124
	v_cvt_pk_bf16_f32 v58, v125, v126
	v_cvt_pk_bf16_f32 v59, v127, v128
	ds_read2_b64 v[64:67], v21 offset0:136 offset1:140
	v_add_u32_e32 v21, 0xe000, v22
	ds_read2_b64 v[164:167], v21 offset0:168 offset1:172
	v_add_u32_e32 v21, 0xf800, v22
	ds_read2_b64 v[168:171], v21 offset0:200 offset1:204
	v_add_u32_e32 v21, 0xcc40, v22
	v_add_u32_e32 v21, 0x4800, v21
	ds_read2_b64 v[172:175], v21 offset0:96 offset1:100
	s_waitcnt lgkmcnt(3)
	v_mfma_f32_16x16x32_bf16 v[32:35], v[64:67], v[56:59], v[32:35]
	s_waitcnt lgkmcnt(2)
	v_mfma_f32_16x16x32_bf16 v[28:31], v[164:167], v[56:59], v[28:31]
	s_waitcnt lgkmcnt(1)
	v_mfma_f32_16x16x32_bf16 v[24:27], v[168:171], v[56:59], v[24:27]
	s_waitcnt lgkmcnt(0)
	v_mfma_f32_16x16x32_bf16 v[16:19], v[172:175], v[56:59], v[16:19]
.LBB0_684:
	s_andn2_b64 vcc, exec, s[6:7]
	s_cbranch_vccnz .LBB0_688
	s_movk_i32 s14, 0x190
	v_mad_u64_u32 v[22:23], s[14:15], v77, s14, v[78:79]
	v_add_u32_e32 v21, 0xc800, v22
	v_cvt_pk_bf16_f32 v56, v107, v108
	v_cvt_pk_bf16_f32 v57, v109, v110
	v_cvt_pk_bf16_f32 v58, v111, v112
	v_cvt_pk_bf16_f32 v59, v113, v114
	ds_read2_b64 v[64:67], v21 offset0:144 offset1:148
	v_add_u32_e32 v21, 0xe000, v22
	ds_read2_b64 v[164:167], v21 offset0:176 offset1:180
	v_add_u32_e32 v21, 0xf800, v22
	ds_read2_b64 v[168:171], v21 offset0:208 offset1:212
	v_add_u32_e32 v21, 0xcc80, v22
	v_add_u32_e32 v21, 0x4800, v21
	ds_read2_b64 v[172:175], v21 offset0:96 offset1:100
	s_waitcnt lgkmcnt(3)
	v_mfma_f32_16x16x32_bf16 v[32:35], v[64:67], v[56:59], v[32:35]
	s_waitcnt lgkmcnt(2)
	v_mfma_f32_16x16x32_bf16 v[28:31], v[164:167], v[56:59], v[28:31]
	s_waitcnt lgkmcnt(1)
	v_mfma_f32_16x16x32_bf16 v[24:27], v[168:171], v[56:59], v[24:27]
	s_waitcnt lgkmcnt(0)
	v_mfma_f32_16x16x32_bf16 v[16:19], v[172:175], v[56:59], v[16:19]
	s_andn2_b64 vcc, exec, s[8:9]
	s_cbranch_vccz .LBB0_689

.LBB0_687:
	s_movk_i32 s14, 0x190
	v_mad_u64_u32 v[22:23], s[14:15], v77, s14, v[78:79]
	v_add_u32_e32 v21, 0xc800, v22
	v_cvt_pk_bf16_f32 v46, v46, v47
	v_cvt_pk_bf16_f32 v47, v48, v49
	v_cvt_pk_bf16_f32 v48, v50, v51
	v_cvt_pk_bf16_f32 v49, v52, v53
	ds_read2_b64 v[50:53], v21 offset0:160 offset1:164
	v_add_u32_e32 v21, 0xe000, v22
	ds_read2_b64 v[164:167], v21 offset0:192 offset1:196
	v_add_u32_e32 v21, 0xf800, v22
	ds_read2_b64 v[168:171], v21 offset0:224 offset1:228
	v_add_u32_e32 v21, 0xcd00, v22
	v_add_u32_e32 v21, 0x4800, v21
	ds_read2_b64 v[172:175], v21 offset0:96 offset1:100
	s_waitcnt lgkmcnt(3)
	v_mfma_f32_16x16x32_bf16 v[32:35], v[50:53], v[46:49], v[32:35]
	s_waitcnt lgkmcnt(2)
	v_mfma_f32_16x16x32_bf16 v[28:31], v[164:167], v[46:49], v[28:31]
	s_waitcnt lgkmcnt(1)
	v_mfma_f32_16x16x32_bf16 v[24:27], v[168:171], v[46:49], v[24:27]
	s_waitcnt lgkmcnt(0)
	v_mfma_f32_16x16x32_bf16 v[16:19], v[172:175], v[46:49], v[16:19]
	s_andn2_b64 vcc, exec, s[12:13]
	s_cbranch_vccz .LBB0_691
	s_branch .LBB0_692

.LBB0_689:
	s_movk_i32 s14, 0x190
	v_mad_u64_u32 v[22:23], s[14:15], v77, s14, v[78:79]
	v_add_u32_e32 v21, 0xc800, v22
	v_cvt_pk_bf16_f32 v54, v54, v55
	v_cvt_pk_bf16_f32 v55, v60, v61
	v_cvt_pk_bf16_f32 v56, v62, v63
	v_cvt_pk_bf16_f32 v57, v105, v106
	ds_read2_b64 v[58:61], v21 offset0:152 offset1:156
	v_add_u32_e32 v21, 0xe000, v22
	ds_read2_b64 v[164:167], v21 offset0:184 offset1:188
	v_add_u32_e32 v21, 0xf800, v22
	ds_read2_b64 v[168:171], v21 offset0:216 offset1:220
	v_add_u32_e32 v21, 0xccc0, v22
	v_add_u32_e32 v21, 0x4800, v21
	ds_read2_b64 v[172:175], v21 offset0:96 offset1:100
	s_waitcnt lgkmcnt(3)
	v_mfma_f32_16x16x32_bf16 v[32:35], v[58:61], v[54:57], v[32:35]
	s_waitcnt lgkmcnt(2)
	v_mfma_f32_16x16x32_bf16 v[28:31], v[164:167], v[54:57], v[28:31]
	s_waitcnt lgkmcnt(1)
	v_mfma_f32_16x16x32_bf16 v[24:27], v[168:171], v[54:57], v[24:27]
	s_waitcnt lgkmcnt(0)
	v_mfma_f32_16x16x32_bf16 v[16:19], v[172:175], v[54:57], v[16:19]
	s_andn2_b64 vcc, exec, s[10:11]
	s_cbranch_vccz .LBB0_687

.LBB0_691:
	s_movk_i32 s14, 0x190
	v_mad_u64_u32 v[22:23], s[14:15], v77, s14, v[78:79]
	v_add_u32_e32 v21, 0xc800, v22
	v_cvt_pk_bf16_f32 v38, v38, v39
	v_cvt_pk_bf16_f32 v39, v40, v41
	v_cvt_pk_bf16_f32 v40, v42, v43
	v_cvt_pk_bf16_f32 v41, v44, v45
	ds_read2_b64 v[42:45], v21 offset0:168 offset1:172
	v_add_u32_e32 v21, 0xe000, v22
	ds_read2_b64 v[164:167], v21 offset0:200 offset1:204
	v_add_u32_e32 v21, 0xf800, v22
	ds_read2_b64 v[168:171], v21 offset0:232 offset1:236
	v_add_u32_e32 v21, 0xcd40, v22
	v_add_u32_e32 v21, 0x4800, v21
	ds_read2_b64 v[172:175], v21 offset0:96 offset1:100
	s_waitcnt lgkmcnt(3)
	v_mfma_f32_16x16x32_bf16 v[32:35], v[42:45], v[38:41], v[32:35]
	s_waitcnt lgkmcnt(2)
	v_mfma_f32_16x16x32_bf16 v[28:31], v[164:167], v[38:41], v[28:31]
	s_waitcnt lgkmcnt(1)
	v_mfma_f32_16x16x32_bf16 v[24:27], v[168:171], v[38:41], v[24:27]
	s_waitcnt lgkmcnt(0)
	v_mfma_f32_16x16x32_bf16 v[16:19], v[172:175], v[38:41], v[16:19]

.LBB0_722:
	s_movk_i32 s14, 0x190
	v_mad_u64_u32 v[58:59], s[14:15], v77, s14, v[78:79]
	v_add_u32_e32 v21, 0xc800, v58
	v_cvt_pk_bf16_f32 v46, v127, v128
	v_cvt_pk_bf16_f32 v47, v129, v130
	v_cvt_pk_bf16_f32 v48, v131, v132
	v_cvt_pk_bf16_f32 v49, v133, v134
	ds_read2_b64 v[54:57], v21 offset0:136 offset1:140
	v_add_u32_e32 v21, 0xe000, v58
	ds_read2_b64 v[164:167], v21 offset0:168 offset1:172
	v_add_u32_e32 v21, 0xf800, v58
	ds_read2_b64 v[168:171], v21 offset0:200 offset1:204
	v_add_u32_e32 v21, 0xcc40, v58
	v_add_u32_e32 v21, 0x4800, v21
	ds_read2_b64 v[172:175], v21 offset0:96 offset1:100
	s_waitcnt lgkmcnt(3)
	v_mfma_f32_16x16x32_bf16 v[22:25], v[54:57], v[46:49], v[22:25]
	s_waitcnt lgkmcnt(2)
	v_mfma_f32_16x16x32_bf16 v[16:19], v[164:167], v[46:49], v[16:19]
	s_waitcnt lgkmcnt(1)
	v_mfma_f32_16x16x32_bf16 v[12:15], v[168:171], v[46:49], v[12:15]
	s_waitcnt lgkmcnt(0)
	v_mfma_f32_16x16x32_bf16 v[8:11], v[172:175], v[46:49], v[8:11]
.LBB0_723:
	s_andn2_b64 vcc, exec, s[6:7]
	s_cbranch_vccnz .LBB0_727
	s_movk_i32 s14, 0x190
	v_mad_u64_u32 v[58:59], s[14:15], v77, s14, v[78:79]
	v_add_u32_e32 v21, 0xc800, v58
	v_cvt_pk_bf16_f32 v46, v113, v114
	v_cvt_pk_bf16_f32 v47, v115, v116
	v_cvt_pk_bf16_f32 v48, v117, v124
	v_cvt_pk_bf16_f32 v49, v125, v126
	ds_read2_b64 v[54:57], v21 offset0:144 offset1:148
	v_add_u32_e32 v21, 0xe000, v58
	ds_read2_b64 v[164:167], v21 offset0:176 offset1:180
	v_add_u32_e32 v21, 0xf800, v58
	ds_read2_b64 v[168:171], v21 offset0:208 offset1:212
	v_add_u32_e32 v21, 0xcc80, v58
	v_add_u32_e32 v21, 0x4800, v21
	ds_read2_b64 v[172:175], v21 offset0:96 offset1:100
	s_waitcnt lgkmcnt(3)
	v_mfma_f32_16x16x32_bf16 v[22:25], v[54:57], v[46:49], v[22:25]
	s_waitcnt lgkmcnt(2)
	v_mfma_f32_16x16x32_bf16 v[16:19], v[164:167], v[46:49], v[16:19]
	s_waitcnt lgkmcnt(1)
	v_mfma_f32_16x16x32_bf16 v[12:15], v[168:171], v[46:49], v[12:15]
	s_waitcnt lgkmcnt(0)
	v_mfma_f32_16x16x32_bf16 v[8:11], v[172:175], v[46:49], v[8:11]
	s_andn2_b64 vcc, exec, s[8:9]
	s_cbranch_vccz .LBB0_728

.LBB0_726:
	s_movk_i32 s14, 0x190
	v_mad_u64_u32 v[44:45], s[14:15], v77, s14, v[78:79]
	v_add_u32_e32 v21, 0xc800, v44
	v_cvt_pk_bf16_f32 v36, v36, v37
	v_cvt_pk_bf16_f32 v37, v38, v39
	v_cvt_pk_bf16_f32 v38, v40, v41
	v_cvt_pk_bf16_f32 v39, v42, v43
	ds_read2_b64 v[40:43], v21 offset0:160 offset1:164
	v_add_u32_e32 v21, 0xe000, v44
	ds_read2_b64 v[164:167], v21 offset0:192 offset1:196
	v_add_u32_e32 v21, 0xf800, v44
	ds_read2_b64 v[168:171], v21 offset0:224 offset1:228
	v_add_u32_e32 v21, 0xcd00, v44
	v_add_u32_e32 v21, 0x4800, v21
	ds_read2_b64 v[172:175], v21 offset0:96 offset1:100
	s_waitcnt lgkmcnt(3)
	v_mfma_f32_16x16x32_bf16 v[22:25], v[40:43], v[36:39], v[22:25]
	s_waitcnt lgkmcnt(2)
	v_mfma_f32_16x16x32_bf16 v[16:19], v[164:167], v[36:39], v[16:19]
	s_waitcnt lgkmcnt(1)
	v_mfma_f32_16x16x32_bf16 v[12:15], v[168:171], v[36:39], v[12:15]
	s_waitcnt lgkmcnt(0)
	v_mfma_f32_16x16x32_bf16 v[8:11], v[172:175], v[36:39], v[8:11]
	s_andn2_b64 vcc, exec, s[12:13]
	s_cbranch_vccz .LBB0_730
	s_branch .LBB0_731

.LBB0_728:
	s_movk_i32 s14, 0x190
	v_cvt_pk_bf16_f32 v44, v44, v45
	v_cvt_pk_bf16_f32 v45, v50, v51
	v_cvt_pk_bf16_f32 v46, v52, v53
	v_mad_u64_u32 v[52:53], s[14:15], v77, s14, v[78:79]
	v_add_u32_e32 v21, 0xc800, v52
	v_cvt_pk_bf16_f32 v47, v111, v112
	ds_read2_b64 v[48:51], v21 offset0:152 offset1:156
	v_add_u32_e32 v21, 0xe000, v52
	ds_read2_b64 v[164:167], v21 offset0:184 offset1:188
	v_add_u32_e32 v21, 0xf800, v52
	ds_read2_b64 v[168:171], v21 offset0:216 offset1:220
	v_add_u32_e32 v21, 0xccc0, v52
	v_add_u32_e32 v21, 0x4800, v21
	ds_read2_b64 v[172:175], v21 offset0:96 offset1:100
	s_waitcnt lgkmcnt(3)
	v_mfma_f32_16x16x32_bf16 v[22:25], v[48:51], v[44:47], v[22:25]
	s_waitcnt lgkmcnt(2)
	v_mfma_f32_16x16x32_bf16 v[16:19], v[164:167], v[44:47], v[16:19]
	s_waitcnt lgkmcnt(1)
	v_mfma_f32_16x16x32_bf16 v[12:15], v[168:171], v[44:47], v[12:15]
	s_waitcnt lgkmcnt(0)
	v_mfma_f32_16x16x32_bf16 v[8:11], v[172:175], v[44:47], v[8:11]
	s_andn2_b64 vcc, exec, s[10:11]
	s_cbranch_vccz .LBB0_726

.LBB0_730:
	s_movk_i32 s14, 0x190
	v_mad_u64_u32 v[36:37], s[14:15], v77, s14, v[78:79]
	v_add_u32_e32 v21, 0xc800, v36
	v_cvt_pk_bf16_f32 v28, v28, v29
	v_cvt_pk_bf16_f32 v29, v30, v31
	v_cvt_pk_bf16_f32 v30, v32, v33
	v_cvt_pk_bf16_f32 v31, v34, v35
	ds_read2_b64 v[32:35], v21 offset0:168 offset1:172
	v_add_u32_e32 v21, 0xe000, v36
	ds_read2_b64 v[164:167], v21 offset0:200 offset1:204
	v_add_u32_e32 v21, 0xf800, v36
	ds_read2_b64 v[168:171], v21 offset0:232 offset1:236
	v_add_u32_e32 v21, 0xcd40, v36
	v_add_u32_e32 v21, 0x4800, v21
	ds_read2_b64 v[172:175], v21 offset0:96 offset1:100
	s_waitcnt lgkmcnt(3)
	v_mfma_f32_16x16x32_bf16 v[22:25], v[32:35], v[28:31], v[22:25]
	s_waitcnt lgkmcnt(2)
	v_mfma_f32_16x16x32_bf16 v[16:19], v[164:167], v[28:31], v[16:19]
	s_waitcnt lgkmcnt(1)
	v_mfma_f32_16x16x32_bf16 v[12:15], v[168:171], v[28:31], v[12:15]
	s_waitcnt lgkmcnt(0)
	v_mfma_f32_16x16x32_bf16 v[8:11], v[172:175], v[28:31], v[8:11]

.LBB0_761:
	s_movk_i32 s4, 0x190
	v_mad_u64_u32 v[22:23], s[4:5], v77, s4, v[78:79]
	v_add_u32_e32 v21, 0xc800, v22
	v_cvt_pk_bf16_f32 v38, v136, v137
	v_cvt_pk_bf16_f32 v39, v138, v139
	v_cvt_pk_bf16_f32 v40, v140, v141
	v_cvt_pk_bf16_f32 v41, v142, v143
	ds_read2_b64 v[46:49], v21 offset0:136 offset1:140
	v_add_u32_e32 v21, 0xe000, v22
	ds_read2_b64 v[164:167], v21 offset0:168 offset1:172
	v_add_u32_e32 v21, 0xf800, v22
	ds_read2_b64 v[168:171], v21 offset0:200 offset1:204
	v_add_u32_e32 v21, 0xcc40, v22
	v_add_u32_e32 v21, 0x4800, v21
	ds_read2_b64 v[172:175], v21 offset0:96 offset1:100
	s_waitcnt lgkmcnt(3)
	v_mfma_f32_16x16x32_bf16 v[12:15], v[46:49], v[38:41], v[12:15]
	s_waitcnt lgkmcnt(2)
	v_mfma_f32_16x16x32_bf16 v[8:11], v[164:167], v[38:41], v[8:11]
	s_waitcnt lgkmcnt(1)
	v_mfma_f32_16x16x32_bf16 v[4:7], v[168:171], v[38:41], v[4:7]
	s_waitcnt lgkmcnt(0)
	v_mfma_f32_16x16x32_bf16 v[0:3], v[172:175], v[38:41], v[0:3]
.LBB0_762:
	s_andn2_b64 vcc, exec, s[6:7]
	s_cbranch_vccnz .LBB0_766
	s_movk_i32 s4, 0x190
	v_mad_u64_u32 v[22:23], s[4:5], v77, s4, v[78:79]
	v_add_u32_e32 v21, 0xc800, v22
	v_cvt_pk_bf16_f32 v38, v128, v129
	v_cvt_pk_bf16_f32 v39, v130, v131
	v_cvt_pk_bf16_f32 v40, v132, v133
	v_cvt_pk_bf16_f32 v41, v134, v135
	ds_read2_b64 v[46:49], v21 offset0:144 offset1:148
	v_add_u32_e32 v21, 0xe000, v22
	ds_read2_b64 v[164:167], v21 offset0:176 offset1:180
	v_add_u32_e32 v21, 0xf800, v22
	ds_read2_b64 v[168:171], v21 offset0:208 offset1:212
	v_add_u32_e32 v21, 0xcc80, v22
	v_add_u32_e32 v21, 0x4800, v21
	ds_read2_b64 v[172:175], v21 offset0:96 offset1:100
	s_waitcnt lgkmcnt(3)
	v_mfma_f32_16x16x32_bf16 v[12:15], v[46:49], v[38:41], v[12:15]
	s_waitcnt lgkmcnt(2)
	v_mfma_f32_16x16x32_bf16 v[8:11], v[164:167], v[38:41], v[8:11]
	s_waitcnt lgkmcnt(1)
	v_mfma_f32_16x16x32_bf16 v[4:7], v[168:171], v[38:41], v[4:7]
	s_waitcnt lgkmcnt(0)
	v_mfma_f32_16x16x32_bf16 v[0:3], v[172:175], v[38:41], v[0:3]
	s_andn2_b64 vcc, exec, s[8:9]
	s_cbranch_vccz .LBB0_767

.LBB0_765:
	s_movk_i32 s4, 0x190
	v_mad_u64_u32 v[22:23], s[4:5], v77, s4, v[78:79]
	v_add_u32_e32 v21, 0xc800, v22
	v_cvt_pk_bf16_f32 v30, v30, v31
	v_cvt_pk_bf16_f32 v31, v32, v33
	v_cvt_pk_bf16_f32 v32, v34, v35
	v_cvt_pk_bf16_f32 v33, v36, v37
	ds_read2_b64 v[34:37], v21 offset0:160 offset1:164
	v_add_u32_e32 v21, 0xe000, v22
	ds_read2_b64 v[164:167], v21 offset0:192 offset1:196
	v_add_u32_e32 v21, 0xf800, v22
	ds_read2_b64 v[168:171], v21 offset0:224 offset1:228
	v_add_u32_e32 v21, 0xcd00, v22
	v_add_u32_e32 v21, 0x4800, v21
	ds_read2_b64 v[172:175], v21 offset0:96 offset1:100
	s_waitcnt lgkmcnt(3)
	v_mfma_f32_16x16x32_bf16 v[12:15], v[34:37], v[30:33], v[12:15]
	s_waitcnt lgkmcnt(2)
	v_mfma_f32_16x16x32_bf16 v[8:11], v[164:167], v[30:33], v[8:11]
	s_waitcnt lgkmcnt(1)
	v_mfma_f32_16x16x32_bf16 v[4:7], v[168:171], v[30:33], v[4:7]
	s_waitcnt lgkmcnt(0)
	v_mfma_f32_16x16x32_bf16 v[0:3], v[172:175], v[30:33], v[0:3]
	s_andn2_b64 vcc, exec, s[12:13]
	s_cbranch_vccz .LBB0_769
	s_branch .LBB0_770

.LBB0_767:
	s_movk_i32 s4, 0x190
	v_mad_u64_u32 v[22:23], s[4:5], v77, s4, v[78:79]
	v_add_u32_e32 v21, 0xc800, v22
	v_cvt_pk_bf16_f32 v38, v42, v43
	v_cvt_pk_bf16_f32 v39, v44, v45
	v_cvt_pk_bf16_f32 v40, v124, v125
	v_cvt_pk_bf16_f32 v41, v126, v127
	ds_read2_b64 v[42:45], v21 offset0:152 offset1:156
	v_add_u32_e32 v21, 0xe000, v22
	ds_read2_b64 v[164:167], v21 offset0:184 offset1:188
	v_add_u32_e32 v21, 0xf800, v22
	ds_read2_b64 v[168:171], v21 offset0:216 offset1:220
	v_add_u32_e32 v21, 0xccc0, v22
	v_add_u32_e32 v21, 0x4800, v21
	ds_read2_b64 v[172:175], v21 offset0:96 offset1:100
	s_waitcnt lgkmcnt(3)
	v_mfma_f32_16x16x32_bf16 v[12:15], v[42:45], v[38:41], v[12:15]
	s_waitcnt lgkmcnt(2)
	v_mfma_f32_16x16x32_bf16 v[8:11], v[164:167], v[38:41], v[8:11]
	s_waitcnt lgkmcnt(1)
	v_mfma_f32_16x16x32_bf16 v[4:7], v[168:171], v[38:41], v[4:7]
	s_waitcnt lgkmcnt(0)
	v_mfma_f32_16x16x32_bf16 v[0:3], v[172:175], v[38:41], v[0:3]
	s_andn2_b64 vcc, exec, s[10:11]
	s_cbranch_vccz .LBB0_765

.LBB0_927:
	s_waitcnt lgkmcnt(0)
	s_barrier
	s_and_saveexec_b64 s[4:5], s[38:39]
	s_cbranch_execz .LBB0_782
	v_mov_b32_e32 v2, v75
	s_mov_b32 s16, s13
	s_lshl_b32 s17, s15, 9
	s_add_u32 s40, s70, s17
	s_addc_u32 s41, s71, 0
	s_add_u32 s6, s82, s17
	s_addc_u32 s7, s83, 0
	v_lshlrev_b32_e32 v8, 1, v54
	ds_read2st64_b32 v[122:123], v2 offset1:128
	ds_read2st64_b32 v[124:125], v2 offset0:4 offset1:132
	ds_read2st64_b32 v[126:127], v2 offset0:8 offset1:136
	ds_read2st64_b32 v[128:129], v2 offset0:12 offset1:140
	ds_read2st64_b32 v[130:131], v2 offset0:16 offset1:144
	ds_read2st64_b32 v[132:133], v2 offset0:20 offset1:148
	ds_read2st64_b32 v[134:135], v2 offset0:24 offset1:152
	ds_read2st64_b32 v[136:137], v2 offset0:28 offset1:156
	ds_read2st64_b32 v[138:139], v2 offset0:32 offset1:160
	ds_read2st64_b32 v[140:141], v2 offset0:36 offset1:164
	ds_read2st64_b32 v[142:143], v2 offset0:40 offset1:168
	ds_read2st64_b32 v[144:145], v2 offset0:44 offset1:172
	ds_read2st64_b32 v[146:147], v2 offset0:48 offset1:176
	ds_read2st64_b32 v[148:149], v2 offset0:52 offset1:180
	ds_read2st64_b32 v[162:163], v2 offset0:56 offset1:184
	ds_read2st64_b32 v[164:165], v2 offset0:60 offset1:188
	ds_read2st64_b32 v[166:167], v2 offset0:64 offset1:192
	ds_read2st64_b32 v[168:169], v2 offset0:68 offset1:196
	ds_read2st64_b32 v[170:171], v2 offset0:72 offset1:200
	ds_read2st64_b32 v[172:173], v2 offset0:76 offset1:204
	ds_read2st64_b32 v[174:175], v2 offset0:80 offset1:208
	ds_read2st64_b32 v[176:177], v2 offset0:84 offset1:212
	ds_read2st64_b32 v[178:179], v2 offset0:88 offset1:216
	ds_read2st64_b32 v[180:181], v2 offset0:92 offset1:220
	ds_read2st64_b32 v[182:183], v2 offset0:96 offset1:224
	ds_read2st64_b32 v[184:185], v2 offset0:100 offset1:228
	ds_read2st64_b32 v[186:187], v2 offset0:104 offset1:232
	ds_read2st64_b32 v[188:189], v2 offset0:108 offset1:236
	ds_read2st64_b32 v[208:209], v2 offset0:112 offset1:240
	ds_read2st64_b32 v[210:211], v2 offset0:116 offset1:244
	ds_read2st64_b32 v[212:213], v2 offset0:120 offset1:248
	ds_read2st64_b32 v[214:215], v2 offset0:124 offset1:252
	s_waitcnt lgkmcnt(15)
	v_fmac_f32_e32 v122, v76, v123
	v_mul_f32_e32 v21, v21, v123
	v_cvt_pk_bf16_f32 v9, v122, v20
	v_cvt_pk_bf16_f32 v10, v21, v20
	v_mov_b32_e32 v76, v122
	global_store_short v8, v9, s[40:41]
	global_store_short v8, v10, s[6:7]
	s_add_i32 s16, s16, -1
	s_cmp_lg_u32 s16, 0
	s_cbranch_scc0 .Llru_scan_done
	s_waitcnt lgkmcnt(15)
	v_fmac_f32_e32 v124, v76, v125
	v_mul_f32_e32 v21, v21, v125
	v_cvt_pk_bf16_f32 v9, v124, v20
	v_cvt_pk_bf16_f32 v10, v21, v20
	v_mov_b32_e32 v76, v124
	global_store_short v8, v9, s[40:41] offset:512
	global_store_short v8, v10, s[6:7] offset:512
	s_add_i32 s16, s16, -1
	s_cmp_lg_u32 s16, 0
	s_cbranch_scc0 .Llru_scan_done
	s_waitcnt lgkmcnt(15)
	v_fmac_f32_e32 v126, v76, v127
	v_mul_f32_e32 v21, v21, v127
	v_cvt_pk_bf16_f32 v9, v126, v20
	v_cvt_pk_bf16_f32 v10, v21, v20
	v_mov_b32_e32 v76, v126
	global_store_short v8, v9, s[40:41] offset:1024
	global_store_short v8, v10, s[6:7] offset:1024
	s_add_i32 s16, s16, -1
	s_cmp_lg_u32 s16, 0
	s_cbranch_scc0 .Llru_scan_done
	s_waitcnt lgkmcnt(15)
	v_fmac_f32_e32 v128, v76, v129
	v_mul_f32_e32 v21, v21, v129
	v_cvt_pk_bf16_f32 v9, v128, v20
	v_cvt_pk_bf16_f32 v10, v21, v20
	v_mov_b32_e32 v76, v128
	global_store_short v8, v9, s[40:41] offset:1536
	global_store_short v8, v10, s[6:7] offset:1536
	s_add_i32 s16, s16, -1
	s_cmp_lg_u32 s16, 0
	s_cbranch_scc0 .Llru_scan_done
	s_waitcnt lgkmcnt(15)
	v_fmac_f32_e32 v130, v76, v131
	v_mul_f32_e32 v21, v21, v131
	v_cvt_pk_bf16_f32 v9, v130, v20
	v_cvt_pk_bf16_f32 v10, v21, v20
	v_mov_b32_e32 v76, v130
	global_store_short v8, v9, s[40:41] offset:2048
	global_store_short v8, v10, s[6:7] offset:2048
	s_add_i32 s16, s16, -1
	s_cmp_lg_u32 s16, 0
	s_cbranch_scc0 .Llru_scan_done
	s_waitcnt lgkmcnt(15)
	v_fmac_f32_e32 v132, v76, v133
	v_mul_f32_e32 v21, v21, v133
	v_cvt_pk_bf16_f32 v9, v132, v20
	v_cvt_pk_bf16_f32 v10, v21, v20
	v_mov_b32_e32 v76, v132
	global_store_short v8, v9, s[40:41] offset:2560
	global_store_short v8, v10, s[6:7] offset:2560
	s_add_i32 s16, s16, -1
	s_cmp_lg_u32 s16, 0
	s_cbranch_scc0 .Llru_scan_done
	s_waitcnt lgkmcnt(15)
	v_fmac_f32_e32 v134, v76, v135
	v_mul_f32_e32 v21, v21, v135
	v_cvt_pk_bf16_f32 v9, v134, v20
	v_cvt_pk_bf16_f32 v10, v21, v20
	v_mov_b32_e32 v76, v134
	global_store_short v8, v9, s[40:41] offset:3072
	global_store_short v8, v10, s[6:7] offset:3072
	s_add_i32 s16, s16, -1
	s_cmp_lg_u32 s16, 0
	s_cbranch_scc0 .Llru_scan_done
	s_waitcnt lgkmcnt(15)
	v_fmac_f32_e32 v136, v76, v137
	v_mul_f32_e32 v21, v21, v137
	v_cvt_pk_bf16_f32 v9, v136, v20
	v_cvt_pk_bf16_f32 v10, v21, v20
	v_mov_b32_e32 v76, v136
	global_store_short v8, v9, s[40:41] offset:3584
	global_store_short v8, v10, s[6:7] offset:3584
	s_add_u32 s40, s40, 0x1000
	s_addc_u32 s41, s41, 0
	s_add_u32 s6, s6, 0x1000
	s_addc_u32 s7, s7, 0
	s_add_i32 s16, s16, -1
	s_cmp_lg_u32 s16, 0
	s_cbranch_scc0 .Llru_scan_done
	s_waitcnt lgkmcnt(15)
	v_fmac_f32_e32 v138, v76, v139
	v_mul_f32_e32 v21, v21, v139
	v_cvt_pk_bf16_f32 v9, v138, v20
	v_cvt_pk_bf16_f32 v10, v21, v20
	v_mov_b32_e32 v76, v138
	global_store_short v8, v9, s[40:41]
	global_store_short v8, v10, s[6:7]
	s_add_i32 s16, s16, -1
	s_cmp_lg_u32 s16, 0
	s_cbranch_scc0 .Llru_scan_done
	s_waitcnt lgkmcnt(15)
	v_fmac_f32_e32 v140, v76, v141
	v_mul_f32_e32 v21, v21, v141
	v_cvt_pk_bf16_f32 v9, v140, v20
	v_cvt_pk_bf16_f32 v10, v21, v20
	v_mov_b32_e32 v76, v140
	global_store_short v8, v9, s[40:41] offset:512
	global_store_short v8, v10, s[6:7] offset:512
	s_add_i32 s16, s16, -1
	s_cmp_lg_u32 s16, 0
	s_cbranch_scc0 .Llru_scan_done
	s_waitcnt lgkmcnt(15)
	v_fmac_f32_e32 v142, v76, v143
	v_mul_f32_e32 v21, v21, v143
	v_cvt_pk_bf16_f32 v9, v142, v20
	v_cvt_pk_bf16_f32 v10, v21, v20
	v_mov_b32_e32 v76, v142
	global_store_short v8, v9, s[40:41] offset:1024
	global_store_short v8, v10, s[6:7] offset:1024
	s_add_i32 s16, s16, -1
	s_cmp_lg_u32 s16, 0
	s_cbranch_scc0 .Llru_scan_done
	s_waitcnt lgkmcnt(15)
	v_fmac_f32_e32 v144, v76, v145
	v_mul_f32_e32 v21, v21, v145
	v_cvt_pk_bf16_f32 v9, v144, v20
	v_cvt_pk_bf16_f32 v10, v21, v20
	v_mov_b32_e32 v76, v144
	global_store_short v8, v9, s[40:41] offset:1536
	global_store_short v8, v10, s[6:7] offset:1536
	s_add_i32 s16, s16, -1
	s_cmp_lg_u32 s16, 0
	s_cbranch_scc0 .Llru_scan_done
	s_waitcnt lgkmcnt(15)
	v_fmac_f32_e32 v146, v76, v147
	v_mul_f32_e32 v21, v21, v147
	v_cvt_pk_bf16_f32 v9, v146, v20
	v_cvt_pk_bf16_f32 v10, v21, v20
	v_mov_b32_e32 v76, v146
	global_store_short v8, v9, s[40:41] offset:2048
	global_store_short v8, v10, s[6:7] offset:2048
	s_add_i32 s16, s16, -1
	s_cmp_lg_u32 s16, 0
	s_cbranch_scc0 .Llru_scan_done
	s_waitcnt lgkmcnt(15)
	v_fmac_f32_e32 v148, v76, v149
	v_mul_f32_e32 v21, v21, v149
	v_cvt_pk_bf16_f32 v9, v148, v20
	v_cvt_pk_bf16_f32 v10, v21, v20
	v_mov_b32_e32 v76, v148
	global_store_short v8, v9, s[40:41] offset:2560
	global_store_short v8, v10, s[6:7] offset:2560
	s_add_i32 s16, s16, -1
	s_cmp_lg_u32 s16, 0
	s_cbranch_scc0 .Llru_scan_done
	s_waitcnt lgkmcnt(15)
	v_fmac_f32_e32 v162, v76, v163
	v_mul_f32_e32 v21, v21, v163
	v_cvt_pk_bf16_f32 v9, v162, v20
	v_cvt_pk_bf16_f32 v10, v21, v20
	v_mov_b32_e32 v76, v162
	global_store_short v8, v9, s[40:41] offset:3072
	global_store_short v8, v10, s[6:7] offset:3072
	s_add_i32 s16, s16, -1
	s_cmp_lg_u32 s16, 0
	s_cbranch_scc0 .Llru_scan_done
	s_waitcnt lgkmcnt(15)
	v_fmac_f32_e32 v164, v76, v165
	v_mul_f32_e32 v21, v21, v165
	v_cvt_pk_bf16_f32 v9, v164, v20
	v_cvt_pk_bf16_f32 v10, v21, v20
	v_mov_b32_e32 v76, v164
	global_store_short v8, v9, s[40:41] offset:3584
	global_store_short v8, v10, s[6:7] offset:3584
	s_add_u32 s40, s40, 0x1000
	s_addc_u32 s41, s41, 0
	s_add_u32 s6, s6, 0x1000
	s_addc_u32 s7, s7, 0
	s_add_i32 s16, s16, -1
	s_cmp_lg_u32 s16, 0
	s_cbranch_scc0 .Llru_scan_done
	s_waitcnt lgkmcnt(15)
	v_fmac_f32_e32 v166, v76, v167
	v_mul_f32_e32 v21, v21, v167
	v_cvt_pk_bf16_f32 v9, v166, v20
	v_cvt_pk_bf16_f32 v10, v21, v20
	v_mov_b32_e32 v76, v166
	global_store_short v8, v9, s[40:41]
	global_store_short v8, v10, s[6:7]
	s_add_i32 s16, s16, -1
	s_cmp_lg_u32 s16, 0
	s_cbranch_scc0 .Llru_scan_done
	s_waitcnt lgkmcnt(14)
	v_fmac_f32_e32 v168, v76, v169
	v_mul_f32_e32 v21, v21, v169
	v_cvt_pk_bf16_f32 v9, v168, v20
	v_cvt_pk_bf16_f32 v10, v21, v20
	v_mov_b32_e32 v76, v168
	global_store_short v8, v9, s[40:41] offset:512
	global_store_short v8, v10, s[6:7] offset:512
	s_add_i32 s16, s16, -1
	s_cmp_lg_u32 s16, 0
	s_cbranch_scc0 .Llru_scan_done
	s_waitcnt lgkmcnt(13)
	v_fmac_f32_e32 v170, v76, v171
	v_mul_f32_e32 v21, v21, v171
	v_cvt_pk_bf16_f32 v9, v170, v20
	v_cvt_pk_bf16_f32 v10, v21, v20
	v_mov_b32_e32 v76, v170
	global_store_short v8, v9, s[40:41] offset:1024
	global_store_short v8, v10, s[6:7] offset:1024
	s_add_i32 s16, s16, -1
	s_cmp_lg_u32 s16, 0
	s_cbranch_scc0 .Llru_scan_done
	s_waitcnt lgkmcnt(12)
	v_fmac_f32_e32 v172, v76, v173
	v_mul_f32_e32 v21, v21, v173
	v_cvt_pk_bf16_f32 v9, v172, v20
	v_cvt_pk_bf16_f32 v10, v21, v20
	v_mov_b32_e32 v76, v172
	global_store_short v8, v9, s[40:41] offset:1536
	global_store_short v8, v10, s[6:7] offset:1536
	s_add_i32 s16, s16, -1
	s_cmp_lg_u32 s16, 0
	s_cbranch_scc0 .Llru_scan_done
	s_waitcnt lgkmcnt(11)
	v_fmac_f32_e32 v174, v76, v175
	v_mul_f32_e32 v21, v21, v175
	v_cvt_pk_bf16_f32 v9, v174, v20
	v_cvt_pk_bf16_f32 v10, v21, v20
	v_mov_b32_e32 v76, v174
	global_store_short v8, v9, s[40:41] offset:2048
	global_store_short v8, v10, s[6:7] offset:2048
	s_add_i32 s16, s16, -1
	s_cmp_lg_u32 s16, 0
	s_cbranch_scc0 .Llru_scan_done
	s_waitcnt lgkmcnt(10)
	v_fmac_f32_e32 v176, v76, v177
	v_mul_f32_e32 v21, v21, v177
	v_cvt_pk_bf16_f32 v9, v176, v20
	v_cvt_pk_bf16_f32 v10, v21, v20
	v_mov_b32_e32 v76, v176
	global_store_short v8, v9, s[40:41] offset:2560
	global_store_short v8, v10, s[6:7] offset:2560
	s_add_i32 s16, s16, -1
	s_cmp_lg_u32 s16, 0
	s_cbranch_scc0 .Llru_scan_done
	s_waitcnt lgkmcnt(9)
	v_fmac_f32_e32 v178, v76, v179
	v_mul_f32_e32 v21, v21, v179
	v_cvt_pk_bf16_f32 v9, v178, v20
	v_cvt_pk_bf16_f32 v10, v21, v20
	v_mov_b32_e32 v76, v178
	global_store_short v8, v9, s[40:41] offset:3072
	global_store_short v8, v10, s[6:7] offset:3072
	s_add_i32 s16, s16, -1
	s_cmp_lg_u32 s16, 0
	s_cbranch_scc0 .Llru_scan_done
	s_waitcnt lgkmcnt(8)
	v_fmac_f32_e32 v180, v76, v181
	v_mul_f32_e32 v21, v21, v181
	v_cvt_pk_bf16_f32 v9, v180, v20
	v_cvt_pk_bf16_f32 v10, v21, v20
	v_mov_b32_e32 v76, v180
	global_store_short v8, v9, s[40:41] offset:3584
	global_store_short v8, v10, s[6:7] offset:3584
	s_add_u32 s40, s40, 0x1000
	s_addc_u32 s41, s41, 0
	s_add_u32 s6, s6, 0x1000
	s_addc_u32 s7, s7, 0
	s_add_i32 s16, s16, -1
	s_cmp_lg_u32 s16, 0
	s_cbranch_scc0 .Llru_scan_done
	s_waitcnt lgkmcnt(7)
	v_fmac_f32_e32 v182, v76, v183
	v_mul_f32_e32 v21, v21, v183
	v_cvt_pk_bf16_f32 v9, v182, v20
	v_cvt_pk_bf16_f32 v10, v21, v20
	v_mov_b32_e32 v76, v182
	global_store_short v8, v9, s[40:41]
	global_store_short v8, v10, s[6:7]
	s_add_i32 s16, s16, -1
	s_cmp_lg_u32 s16, 0
	s_cbranch_scc0 .Llru_scan_done
	s_waitcnt lgkmcnt(6)
	v_fmac_f32_e32 v184, v76, v185
	v_mul_f32_e32 v21, v21, v185
	v_cvt_pk_bf16_f32 v9, v184, v20
	v_cvt_pk_bf16_f32 v10, v21, v20
	v_mov_b32_e32 v76, v184
	global_store_short v8, v9, s[40:41] offset:512
	global_store_short v8, v10, s[6:7] offset:512
	s_add_i32 s16, s16, -1
	s_cmp_lg_u32 s16, 0
	s_cbranch_scc0 .Llru_scan_done
	s_waitcnt lgkmcnt(5)
	v_fmac_f32_e32 v186, v76, v187
	v_mul_f32_e32 v21, v21, v187
	v_cvt_pk_bf16_f32 v9, v186, v20
	v_cvt_pk_bf16_f32 v10, v21, v20
	v_mov_b32_e32 v76, v186
	global_store_short v8, v9, s[40:41] offset:1024
	global_store_short v8, v10, s[6:7] offset:1024
	s_add_i32 s16, s16, -1
	s_cmp_lg_u32 s16, 0
	s_cbranch_scc0 .Llru_scan_done
	s_waitcnt lgkmcnt(4)
	v_fmac_f32_e32 v188, v76, v189
	v_mul_f32_e32 v21, v21, v189
	v_cvt_pk_bf16_f32 v9, v188, v20
	v_cvt_pk_bf16_f32 v10, v21, v20
	v_mov_b32_e32 v76, v188
	global_store_short v8, v9, s[40:41] offset:1536
	global_store_short v8, v10, s[6:7] offset:1536
	s_add_i32 s16, s16, -1
	s_cmp_lg_u32 s16, 0
	s_cbranch_scc0 .Llru_scan_done
	s_waitcnt lgkmcnt(3)
	v_fmac_f32_e32 v208, v76, v209
	v_mul_f32_e32 v21, v21, v209
	v_cvt_pk_bf16_f32 v9, v208, v20
	v_cvt_pk_bf16_f32 v10, v21, v20
	v_mov_b32_e32 v76, v208
	global_store_short v8, v9, s[40:41] offset:2048
	global_store_short v8, v10, s[6:7] offset:2048
	s_add_i32 s16, s16, -1
	s_cmp_lg_u32 s16, 0
	s_cbranch_scc0 .Llru_scan_done
	s_waitcnt lgkmcnt(2)
	v_fmac_f32_e32 v210, v76, v211
	v_mul_f32_e32 v21, v21, v211
	v_cvt_pk_bf16_f32 v9, v210, v20
	v_cvt_pk_bf16_f32 v10, v21, v20
	v_mov_b32_e32 v76, v210
	global_store_short v8, v9, s[40:41] offset:2560
	global_store_short v8, v10, s[6:7] offset:2560
	s_add_i32 s16, s16, -1
	s_cmp_lg_u32 s16, 0
	s_cbranch_scc0 .Llru_scan_done
	s_waitcnt lgkmcnt(1)
	v_fmac_f32_e32 v212, v76, v213
	v_mul_f32_e32 v21, v21, v213
	v_cvt_pk_bf16_f32 v9, v212, v20
	v_cvt_pk_bf16_f32 v10, v21, v20
	v_mov_b32_e32 v76, v212
	global_store_short v8, v9, s[40:41] offset:3072
	global_store_short v8, v10, s[6:7] offset:3072
	s_add_i32 s16, s16, -1
	s_cmp_lg_u32 s16, 0
	s_cbranch_scc0 .Llru_scan_done
	s_waitcnt lgkmcnt(0)
	v_fmac_f32_e32 v214, v76, v215
	v_mul_f32_e32 v21, v21, v215
	v_cvt_pk_bf16_f32 v9, v214, v20
	v_cvt_pk_bf16_f32 v10, v21, v20
	v_mov_b32_e32 v76, v214
	global_store_short v8, v9, s[40:41] offset:3584
	global_store_short v8, v10, s[6:7] offset:3584
.Llru_scan_done:
	s_branch .LBB0_782
.LBB0_931:
	s_or_saveexec_b64 s[6:7], s[6:7]
	v_mov_b64_e32 v[12:13], s[84:85]
	s_xor_b64 exec, exec, s[6:7]
	s_cbranch_execz .LBB0_836
